# gate/up GEMM epilogue copies, one 12KB row group per wave per unit (5 rounds); in-loop slots removed
# speedup vs baseline: 1.0044x; 1.0044x over previous
.LBB0_1209:
	v_readlane_b32 s10, v240, 0
	s_add_i32 s12, s8, s10
	s_lshl_b32 s8, s95, 8
	s_add_i32 s8, s8, s15
	s_ashr_i32 s9, s8, 7
	v_readlane_b32 s11, v240, 1
	s_mul_hi_i32 s10, s9, 0x55555556
	s_lshr_b32 s11, s10, 31
	s_add_i32 s10, s10, s11
	s_mul_i32 s11, s14, 3
	s_add_i32 s11, s10, s11
	s_mul_i32 s10, s10, 3
	s_mul_i32 s11, s11, 3
	s_sub_i32 s10, s9, s10
	s_add_i32 s11, s11, s10
	s_mul_hi_i32 s10, s8, 0x30c30c31
	s_lshr_b32 s16, s10, 31
	s_ashr_i32 s10, s10, 4
	s_add_i32 s10, s10, s16
	s_lshl_b32 s16, s10, 3
	s_or_b32 s16, s16, s14
	s_mulk_i32 s10, 0x54
	s_mulk_i32 s16, 0x54
	s_sub_i32 s10, s8, s10
	s_add_i32 s13, s12, 0x2a00
	s_add_i32 s96, s12, 0xffffe000
	s_add_i32 s16, s16, s10
	s_cmp_lt_u32 s9, 12
	s_cselect_b32 s10, s19, s2
	s_add_i32 s10, s10, s9
	s_cmp_lt_i32 s9, 9
	s_cselect_b32 s9, s11, s10
	s_lshl_b32 s9, s9, 7
	s_add_i32 s17, s9, s35
	s_cmpk_lt_i32 s8, 0x540
	s_cselect_b32 s10, s16, -1
	s_and_b64 s[8:9], s[58:59], exec
	s_cselect_b32 s16, s12, s10
	s_cmpk_gt_i32 s12, 0x29ff
	s_cselect_b64 s[8:9], -1, 0
	s_and_b64 s[10:11], s[8:9], exec
	s_cselect_b32 s97, -1, s16
	s_or_b64 s[8:9], s[8:9], s[58:59]
	s_cmpk_lt_u32 s96, 0x1800
	s_cselect_b64 s[10:11], -1, 0
	s_and_b64 s[74:75], s[8:9], s[10:11]
	s_and_b64 s[8:9], s[58:59], exec
	s_cselect_b32 s8, s13, s17
	s_cmpk_lt_i32 s12, 0x3800
	s_mov_b32 s40, s82
	s_cselect_b32 s52, s8, -1
	s_mov_b64 s[76:77], -1
	s_mov_b32 s10, s57
	s_branch .LBB0_1212

.LBB0_1649:
	s_or_b64 exec, exec, s[6:7]
	s_add_u32 s8, s30, 0xfc00000
	s_addc_u32 s9, s31, 0
	v_mov_b32_e32 v10, v164
	s_waitcnt lgkmcnt(0)
	s_barrier
	s_cmpk_gt_i32 s69, 0x5d7
	v_readfirstlane_b32 s7, v10
	s_cbranch_scc1 .LBB0_1665
	v_writelane_b32 v247, s78, 0
	v_writelane_b32 v247, s79, 1
	v_writelane_b32 v247, s4, 2
	v_writelane_b32 v247, s5, 3
	s_lshr_b32 s32, s69, 7
	s_lshl_b32 s32, s32, 3
	s_load_dwordx2 s[96:97], s[0:1], s32 offset:0x20
	s_load_dwordx2 s[76:77], s[0:1], 0xa0
	s_and_b32 s100, s69, 0x7f
	s_mul_i32 s100, s100, 0x300000
	s_mov_b32 s101, 0x1ee80000
	s_cmp_lt_u32 s69, 0x80
	s_cselect_b32 s101, 0x6e80000, s101
	v_and_b32_e32 v246, 63, v164
	v_lshlrev_b32_e32 v246, 4, v246
	s_waitcnt lgkmcnt(0)
	s_add_u32 s96, s96, s100
	s_addc_u32 s97, s97, 0
	s_add_u32 s96, s96, 0x3000
	s_addc_u32 s97, s97, 0
	s_and_b32 s97, s97, 0xffff
	s_mov_b32 s98, 0x300000
	s_mov_b32 s99, 0x20000
	s_add_u32 s76, s76, s101
	s_addc_u32 s77, s77, 0
	s_add_u32 s76, s76, s100
	s_addc_u32 s77, s77, 0
	s_and_b32 s77, s77, 0xffff
	s_mov_b32 s78, 0x300000
	s_mov_b32 s79, 0x20000
	s_lshr_b32 s32, s7, 6
	s_mul_i32 s101, s32, 0x0
	s_add_u32 s100, s101, 0x0
	s_mul_i32 s5, s32, 0x6000
	s_add_u32 s5, s5, 0x0
	s_mov_b32 s32, 0
	s_mov_b32 s4, 0
	s_mov_b32 s100, 0x70000000
	s_mov_b32 s101, 0x70000000
	v_lshlrev_b32_e32 v0, 4, v10
	v_add_u32_e32 v1, 0x2000, v0
	v_ashrrev_i32_e32 v2, 31, v1
	v_lshrrev_b32_e32 v2, 22, v2
	v_add_u32_e32 v2, v1, v2
	v_ashrrev_i32_e32 v8, 10, v2
	v_mul_i32_i24_e32 v2, 0x400, v8
	v_sub_u32_e32 v1, v1, v2
	v_lshrrev_b32_e32 v2, 4, v1
	v_bitop3_b32 v1, v2, v1, 32 bitop3:0x6c
	v_ashrrev_i32_e32 v2, 31, v1
	v_lshrrev_b32_e32 v2, 26, v2
	v_add_u32_e32 v2, v1, v2
	v_lshlrev_b32_e32 v3, 3, v8
	v_ashrrev_i32_e32 v9, 6, v2
	v_and_b32_e32 v3, -16, v3
	v_add_u32_e32 v3, v9, v3
	v_and_b32_e32 v4, 3, v9
	s_mov_b32 s6, 0x1fffe0
	v_lshrrev_b32_e32 v5, 2, v3
	v_lshlrev_b32_e32 v6, 1, v3
	v_and_b32_e32 v2, 0xc0, v2
	v_and_or_b32 v4, v3, s6, v4
	v_and_b32_e32 v5, 4, v5
	v_and_b32_e32 v6, 24, v6
	v_sub_u32_e32 v1, v1, v2
	v_mov_b32_e32 v2, 1
	v_or3_b32 v4, v4, v5, v6
	v_lshlrev_b32_e32 v5, 5, v8
	v_ashrrev_i16_sdwa v1, v2, sext(v1) dst_sel:DWORD dst_unused:UNUSED_PAD src0_sel:DWORD src1_sel:BYTE_0
	v_and_b32_e32 v5, 32, v5
	v_bfe_i32 v11, v1, 0, 16
	v_add_lshl_u32 v1, v5, v11, 1
	v_lshl_add_u32 v130, v4, 11, v1
	v_lshl_add_u32 v132, v3, 11, v1
	v_bfe_i32 v1, v10, 27, 1
	v_lshrrev_b32_e32 v1, 22, v1
	v_add_u32_e32 v1, v0, v1
	v_and_b32_e32 v1, 0xfffffc00, v1
	v_sub_u32_e32 v0, v0, v1
	v_lshrrev_b32_e32 v1, 4, v0
	v_ashrrev_i32_e32 v3, 31, v10
	v_bitop3_b32 v0, v1, v0, 32 bitop3:0x6c
	v_lshrrev_b32_e32 v3, 26, v3
	v_ashrrev_i32_e32 v1, 31, v0
	v_add_u32_e32 v3, v10, v3
	v_lshrrev_b32_e32 v1, 26, v1
	v_ashrrev_i32_e32 v13, 6, v3
	v_add_u32_e32 v1, v0, v1
	v_lshlrev_b32_e32 v3, 3, v13
	v_ashrrev_i32_e32 v12, 6, v1
	v_and_b32_e32 v3, -16, v3
	v_add_u32_e32 v3, v12, v3
	v_and_b32_e32 v4, 3, v12
	s_ashr_i32 s14, s69, 31
	v_and_or_b32 v4, v3, s6, v4
	s_lshr_b32 s6, s14, 29
	s_add_i32 s6, s69, s6
	s_ashr_i32 s2, s7, 6
	s_ashr_i32 s11, s6, 3
	s_and_b32 s6, s6, -8
	s_ashr_i32 s10, s7, 8
	s_lshl_b32 s3, s2, 10
	s_sub_i32 s6, s69, s6
	s_cmp_lt_i32 s6, 0
	s_movk_i32 s15, 0xbc
	s_cselect_b32 s18, s15, 0xbb
	s_mul_i32 s6, s6, s18
	s_add_i32 s6, s6, s11
	s_mul_hi_i32 s11, s6, 0x2e8ba2e9
	s_lshr_b32 s18, s11, 31
	s_ashr_i32 s11, s11, 5
	v_lshrrev_b32_e32 v5, 2, v3
	v_lshlrev_b32_e32 v6, 1, v3
	v_and_b32_e32 v1, 0xc0, v1
	s_add_i32 s11, s11, s18
	v_and_b32_e32 v5, 4, v5
	v_and_b32_e32 v6, 24, v6
	v_sub_u32_e32 v0, v0, v1
	s_lshl_b32 s22, s11, 3
	v_or3_b32 v4, v4, v5, v6
	v_lshlrev_b32_e32 v5, 5, v13
	v_ashrrev_i16_sdwa v0, v2, sext(v0) dst_sel:DWORD dst_unused:UNUSED_PAD src0_sel:DWORD src1_sel:BYTE_0
	s_sub_i32 s18, 0x44, s22
	s_mulk_i32 s11, 0xb0
	v_and_b32_e32 v5, 32, v5
	v_bfe_i32 v14, v0, 0, 16
	s_min_u32 s23, s18, 8
	s_sub_i32 s11, s6, s11
	v_add_lshl_u32 v0, v5, v14, 1
	s_sext_i32_i16 s6, s11
	v_cvt_f32_ubyte0_e32 v2, s23
	v_lshl_add_u32 v134, v4, 11, v0
	v_cvt_f32_i32_e32 v1, s6
	v_rcp_iflag_f32_e32 v4, v2
	v_lshl_add_u32 v136, v3, 11, v0
	s_ashr_i32 s6, s6, 30
	s_or_b32 s6, s6, 1
	v_mul_f32_e32 v0, v1, v4
	v_trunc_f32_e32 v0, v0
	v_fma_f32 v1, -v0, v2, v1
	v_cvt_i32_f32_e32 v0, v0
	v_cmp_ge_f32_e64 s[18:19], |v1|, v2
	s_and_b64 s[18:19], s[18:19], exec
	s_cselect_b32 s6, s6, 0
	v_readfirstlane_b32 s18, v0
	s_add_i32 s6, s18, s6
	s_mul_i32 s18, s6, s23
	s_sub_i32 s11, s11, s18
	s_sext_i32_i16 s11, s11
	s_add_i32 s56, s22, s11
	s_ashr_i32 s57, s56, 31
	s_bfe_i64 s[18:19], s[6:7], 0x100000
	s_lshl_b64 s[22:23], s[56:57], 19
	s_lshl_b64 s[18:19], s[18:19], 19
	s_add_u32 s60, s92, s18
	s_addc_u32 s61, s93, s19
	s_add_i32 s18, s3, 0
	s_add_i32 m0, s18, 0x10000
	v_mov_b32_e32 v139, 0
	global_load_lds_dwordx4 v134, s[60:61]
	s_add_i32 m0, s18, 0x12000
	s_add_u32 s24, s60, 0x40000
	global_load_lds_dwordx4 v130, s[60:61]
	s_addc_u32 s25, s61, 0
	s_add_i32 m0, s18, 0x14000
	v_mov_b32_e32 v135, v139
	global_load_lds_dwordx4 v134, s[24:25]
	s_add_i32 m0, s18, 0x16000
	s_add_u32 s58, s94, s22
	s_addc_u32 s59, s95, s23
	s_add_i32 s19, s18, 0x2000
	global_load_lds_dwordx4 v130, s[24:25]
	s_mov_b32 m0, s18
	s_add_u32 s22, s58, 0x40000
	global_load_lds_dwordx4 v136, s[58:59]
	s_mov_b32 m0, s19
	s_addc_u32 s23, s59, 0
	s_add_i32 s35, s18, 0x4000
	global_load_lds_dwordx4 v132, s[58:59]
	s_mov_b32 m0, s35
	s_add_i32 s43, s18, 0x6000
	global_load_lds_dwordx4 v136, s[22:23]
	s_mov_b32 m0, s43
	v_mov_b32_e32 v131, v139
	global_load_lds_dwordx4 v132, s[22:23]
	v_mov_b32_e32 v137, v139
	v_mov_b32_e32 v133, v139
	s_cmp_eq_u32 s10, 1
	s_mov_b32 s11, 0
	v_lshl_add_u64 v[6:7], s[60:61], 0, v[134:135]
	v_lshl_add_u64 v[4:5], s[60:61], 0, v[130:131]
	v_lshl_add_u64 v[0:1], s[58:59], 0, v[136:137]
	s_cselect_b64 s[22:23], -1, 0
	s_cmp_lg_u32 s10, 1
	v_lshl_add_u64 v[2:3], s[58:59], 0, v[132:133]
	s_cbranch_scc1 .LBB0_1652
	s_barrier

.LBB0_1661:
	s_add_u32 vcc_lo, s5, 0x1000
	s_add_u32 vcc_hi, s5, 0x2000
	buffer_load_dwordx4 v[166:169], v246, s[96:99], s5 offen nt
	buffer_load_dwordx4 v[170:173], v246, s[96:99], s5 offen offset:1024 nt
	buffer_load_dwordx4 v[174:177], v246, s[96:99], s5 offen offset:2048 nt
	buffer_load_dwordx4 v[178:181], v246, s[96:99], s5 offen offset:3072 nt
	buffer_load_dwordx4 v[182:185], v246, s[96:99], vcc_lo offen nt
	buffer_load_dwordx4 v[186:189], v246, s[96:99], vcc_lo offen offset:1024 nt
	buffer_load_dwordx4 v[190:193], v246, s[96:99], vcc_lo offen offset:2048 nt
	buffer_load_dwordx4 v[194:197], v246, s[96:99], vcc_lo offen offset:3072 nt
	buffer_load_dwordx4 v[198:201], v246, s[96:99], vcc_hi offen nt
	buffer_load_dwordx4 v[202:205], v246, s[96:99], vcc_hi offen offset:1024 nt
	buffer_load_dwordx4 v[206:209], v246, s[96:99], vcc_hi offen offset:2048 nt
	buffer_load_dwordx4 v[210:213], v246, s[96:99], vcc_hi offen offset:3072 nt
	v_mul_f32_e32 v153, 0xbfb8aa3b, v124
	v_exp_f32_e32 v153, v153
	v_mul_f32_e32 v154, 0xbfb8aa3b, v125
	v_exp_f32_e32 v155, v154
	s_lshl_b32 s48, s2, 7
	v_add_f32_e32 v153, 1.0, v153
	v_rcp_f32_e32 v154, v153
	v_add_f32_e32 v153, 1.0, v155
	v_mul_f32_e32 v155, 0xbfb8aa3b, v126
	v_exp_f32_e32 v156, v155
	v_mul_f32_e32 v155, 0xbfb8aa3b, v127
	v_exp_f32_e32 v157, v155
	v_rcp_f32_e32 v155, v153
	v_add_f32_e32 v153, 1.0, v156
	v_rcp_f32_e32 v156, v153
	v_add_f32_e32 v153, 1.0, v157
	v_rcp_f32_e32 v157, v153
	v_pk_mul_f32 v[124:125], v[124:125], v[154:155]
	v_mul_f32_e32 v153, 0xbfb8aa3b, v118
	v_pk_mul_f32 v[120:121], v[120:121], v[124:125]
	v_pk_mul_f32 v[124:125], v[126:127], v[156:157]
	v_mul_f32_e32 v126, 0xbfb8aa3b, v116
	v_mul_f32_e32 v127, 0xbfb8aa3b, v117
	v_exp_f32_e32 v126, v126
	v_exp_f32_e32 v127, v127
	v_exp_f32_e32 v153, v153
	v_mul_f32_e32 v154, 0xbfb8aa3b, v119
	v_exp_f32_e32 v155, v154
	v_add_f32_e32 v126, 1.0, v126
	v_add_f32_e32 v127, 1.0, v127
	v_add_f32_e32 v153, 1.0, v153
	v_rcp_f32_e32 v126, v126
	v_rcp_f32_e32 v127, v127
	v_rcp_f32_e32 v154, v153
	v_add_f32_e32 v153, 1.0, v155
	v_rcp_f32_e32 v155, v153
	v_pk_mul_f32 v[116:117], v[116:117], v[126:127]
	v_lshl_add_u32 v152, s56, 8, v129
	v_pk_mul_f32 v[112:113], v[112:113], v[116:117]
	v_pk_mul_f32 v[116:117], v[118:119], v[154:155]
	s_ashr_i32 s49, s48, 31
	v_pk_mul_f32 v[114:115], v[114:115], v[116:117]
	v_pk_mul_f32 v[122:123], v[122:123], v[124:125]
	v_cvt_pk_bf16_f32 v124, v120, v121
	v_mov_b64_e32 v[120:121], s[8:9]
	v_cvt_pk_bf16_f32 v112, v112, v113
	v_cvt_pk_bf16_f32 v113, v114, v115
	v_mul_f32_e32 v114, 0xbfb8aa3b, v108
	v_mul_f32_e32 v115, 0xbfb8aa3b, v109
	v_cvt_pk_bf16_f32 v125, v122, v123
	v_mad_i64_i32 v[122:123], s[50:51], v152, s66, v[120:121]
	s_lshl_b64 s[56:57], s[48:49], 1
	v_exp_f32_e32 v114, v114
	v_exp_f32_e32 v115, v115
	v_lshl_add_u64 v[122:123], v[122:123], 0, s[56:57]
	v_lshl_add_u64 v[122:123], v[122:123], 0, s[10:11]
	v_lshl_add_u64 v[122:123], v[122:123], 0, v[138:139]
	global_store_dwordx2 v[122:123], v[112:113], off offset:128
	v_add_f32_e32 v112, 1.0, v114
	v_add_f32_e32 v113, 1.0, v115
	v_mul_f32_e32 v114, 0xbfb8aa3b, v110
	v_mul_f32_e32 v115, 0xbfb8aa3b, v111
	v_exp_f32_e32 v114, v114
	v_exp_f32_e32 v115, v115
	v_rcp_f32_e32 v112, v112
	v_rcp_f32_e32 v113, v113
	v_add_f32_e32 v114, 1.0, v114
	v_add_f32_e32 v115, 1.0, v115
	v_rcp_f32_e32 v114, v114
	v_rcp_f32_e32 v115, v115
	v_pk_mul_f32 v[108:109], v[108:109], v[112:113]
	v_or_b32_e32 v116, 16, v152
	v_pk_mul_f32 v[104:105], v[104:105], v[108:109]
	v_pk_mul_f32 v[108:109], v[110:111], v[114:115]
	v_mul_f32_e32 v110, 0xbfb8aa3b, v102
	v_pk_mul_f32 v[106:107], v[106:107], v[108:109]
	v_mul_f32_e32 v108, 0xbfb8aa3b, v100
	v_mul_f32_e32 v109, 0xbfb8aa3b, v101
	v_exp_f32_e32 v108, v108
	v_exp_f32_e32 v109, v109
	v_mul_f32_e32 v111, 0xbfb8aa3b, v103
	v_exp_f32_e32 v110, v110
	v_exp_f32_e32 v111, v111
	v_add_f32_e32 v108, 1.0, v108
	v_add_f32_e32 v109, 1.0, v109
	v_rcp_f32_e32 v108, v108
	v_rcp_f32_e32 v109, v109
	v_add_f32_e32 v110, 1.0, v110
	v_add_f32_e32 v111, 1.0, v111
	v_rcp_f32_e32 v110, v110
	v_rcp_f32_e32 v111, v111
	v_pk_mul_f32 v[100:101], v[100:101], v[108:109]
	v_cvt_pk_bf16_f32 v104, v104, v105
	v_pk_mul_f32 v[96:97], v[96:97], v[100:101]
	v_pk_mul_f32 v[100:101], v[102:103], v[110:111]
	v_cvt_pk_bf16_f32 v96, v96, v97
	v_pk_mul_f32 v[98:99], v[98:99], v[100:101]
	v_cvt_pk_bf16_f32 v105, v106, v107
	v_cvt_pk_bf16_f32 v97, v98, v99
	v_mul_f32_e32 v98, 0xbfb8aa3b, v92
	v_mul_f32_e32 v99, 0xbfb8aa3b, v93
	v_mad_i64_i32 v[106:107], s[48:49], v116, s66, v[120:121]
	v_exp_f32_e32 v98, v98
	v_exp_f32_e32 v99, v99
	v_lshl_add_u64 v[106:107], v[106:107], 0, s[56:57]
	v_lshl_add_u64 v[106:107], v[106:107], 0, s[10:11]
	v_lshl_add_u64 v[106:107], v[106:107], 0, v[138:139]
	global_store_dwordx2 v[106:107], v[96:97], off offset:128
	v_add_f32_e32 v96, 1.0, v98
	v_add_f32_e32 v97, 1.0, v99
	v_mul_f32_e32 v98, 0xbfb8aa3b, v94
	v_mul_f32_e32 v99, 0xbfb8aa3b, v95
	v_exp_f32_e32 v98, v98
	v_exp_f32_e32 v99, v99
	v_rcp_f32_e32 v96, v96
	v_rcp_f32_e32 v97, v97
	v_add_f32_e32 v98, 1.0, v98
	v_add_f32_e32 v99, 1.0, v99
	v_rcp_f32_e32 v98, v98
	v_rcp_f32_e32 v99, v99
	v_pk_mul_f32 v[92:93], v[92:93], v[96:97]
	v_or_b32_e32 v100, 32, v152
	v_pk_mul_f32 v[88:89], v[88:89], v[92:93]
	v_pk_mul_f32 v[92:93], v[94:95], v[98:99]
	v_mul_f32_e32 v94, 0xbfb8aa3b, v86
	v_pk_mul_f32 v[90:91], v[90:91], v[92:93]
	v_mul_f32_e32 v92, 0xbfb8aa3b, v84
	v_mul_f32_e32 v93, 0xbfb8aa3b, v85
	v_exp_f32_e32 v92, v92
	v_exp_f32_e32 v93, v93
	v_mul_f32_e32 v95, 0xbfb8aa3b, v87
	v_exp_f32_e32 v94, v94
	v_exp_f32_e32 v95, v95
	v_add_f32_e32 v92, 1.0, v92
	v_add_f32_e32 v93, 1.0, v93
	v_rcp_f32_e32 v92, v92
	v_rcp_f32_e32 v93, v93
	v_add_f32_e32 v94, 1.0, v94
	v_add_f32_e32 v95, 1.0, v95
	v_rcp_f32_e32 v94, v94
	v_rcp_f32_e32 v95, v95
	v_pk_mul_f32 v[84:85], v[84:85], v[92:93]
	v_cvt_pk_bf16_f32 v88, v88, v89
	v_pk_mul_f32 v[80:81], v[80:81], v[84:85]
	v_pk_mul_f32 v[84:85], v[86:87], v[94:95]
	v_cvt_pk_bf16_f32 v80, v80, v81
	v_pk_mul_f32 v[82:83], v[82:83], v[84:85]
	v_cvt_pk_bf16_f32 v89, v90, v91
	v_cvt_pk_bf16_f32 v81, v82, v83
	v_mul_f32_e32 v82, 0xbfb8aa3b, v76
	v_mul_f32_e32 v83, 0xbfb8aa3b, v77
	v_mad_i64_i32 v[90:91], s[48:49], v100, s66, v[120:121]
	v_exp_f32_e32 v82, v82
	v_exp_f32_e32 v83, v83
	v_lshl_add_u64 v[90:91], v[90:91], 0, s[56:57]
	v_lshl_add_u64 v[90:91], v[90:91], 0, s[10:11]
	v_lshl_add_u64 v[90:91], v[90:91], 0, v[138:139]
	global_store_dwordx2 v[90:91], v[80:81], off offset:128
	v_add_f32_e32 v80, 1.0, v82
	v_add_f32_e32 v81, 1.0, v83
	v_mul_f32_e32 v82, 0xbfb8aa3b, v78
	v_mul_f32_e32 v83, 0xbfb8aa3b, v79
	v_exp_f32_e32 v82, v82
	v_exp_f32_e32 v83, v83
	v_rcp_f32_e32 v80, v80
	v_rcp_f32_e32 v81, v81
	v_add_f32_e32 v82, 1.0, v82
	v_add_f32_e32 v83, 1.0, v83
	v_rcp_f32_e32 v82, v82
	v_rcp_f32_e32 v83, v83
	v_pk_mul_f32 v[76:77], v[76:77], v[80:81]
	v_or_b32_e32 v84, 48, v152
	v_pk_mul_f32 v[72:73], v[72:73], v[76:77]
	v_pk_mul_f32 v[76:77], v[78:79], v[82:83]
	v_mul_f32_e32 v78, 0xbfb8aa3b, v70
	v_pk_mul_f32 v[74:75], v[74:75], v[76:77]
	v_mul_f32_e32 v76, 0xbfb8aa3b, v68
	v_mul_f32_e32 v77, 0xbfb8aa3b, v69
	v_exp_f32_e32 v76, v76
	v_exp_f32_e32 v77, v77
	v_mul_f32_e32 v79, 0xbfb8aa3b, v71
	v_exp_f32_e32 v78, v78
	v_exp_f32_e32 v79, v79
	v_add_f32_e32 v76, 1.0, v76
	v_add_f32_e32 v77, 1.0, v77
	v_rcp_f32_e32 v76, v76
	v_rcp_f32_e32 v77, v77
	v_add_f32_e32 v78, 1.0, v78
	v_add_f32_e32 v79, 1.0, v79
	v_rcp_f32_e32 v78, v78
	v_rcp_f32_e32 v79, v79
	v_pk_mul_f32 v[68:69], v[68:69], v[76:77]
	v_cvt_pk_bf16_f32 v72, v72, v73
	v_pk_mul_f32 v[64:65], v[64:65], v[68:69]
	v_pk_mul_f32 v[68:69], v[70:71], v[78:79]
	v_cvt_pk_bf16_f32 v64, v64, v65
	v_pk_mul_f32 v[66:67], v[66:67], v[68:69]
	v_cvt_pk_bf16_f32 v73, v74, v75
	v_cvt_pk_bf16_f32 v65, v66, v67
	v_mul_f32_e32 v66, 0xbfb8aa3b, v60
	v_mul_f32_e32 v67, 0xbfb8aa3b, v61
	v_mad_i64_i32 v[74:75], s[48:49], v84, s66, v[120:121]
	v_exp_f32_e32 v66, v66
	v_exp_f32_e32 v67, v67
	v_lshl_add_u64 v[74:75], v[74:75], 0, s[56:57]
	v_lshl_add_u64 v[74:75], v[74:75], 0, s[10:11]
	v_lshl_add_u64 v[74:75], v[74:75], 0, v[138:139]
	global_store_dwordx2 v[74:75], v[64:65], off offset:128
	v_add_f32_e32 v64, 1.0, v66
	v_add_f32_e32 v65, 1.0, v67
	v_mul_f32_e32 v66, 0xbfb8aa3b, v62
	v_mul_f32_e32 v67, 0xbfb8aa3b, v63
	v_exp_f32_e32 v66, v66
	v_exp_f32_e32 v67, v67
	v_rcp_f32_e32 v64, v64
	v_rcp_f32_e32 v65, v65
	v_add_f32_e32 v66, 1.0, v66
	v_add_f32_e32 v67, 1.0, v67
	v_rcp_f32_e32 v66, v66
	v_rcp_f32_e32 v67, v67
	v_pk_mul_f32 v[60:61], v[60:61], v[64:65]
	v_add_u32_e32 v68, 0x80, v152
	v_pk_mul_f32 v[56:57], v[56:57], v[60:61]
	v_pk_mul_f32 v[60:61], v[62:63], v[66:67]
	v_mul_f32_e32 v62, 0xbfb8aa3b, v54
	v_pk_mul_f32 v[58:59], v[58:59], v[60:61]
	v_mul_f32_e32 v60, 0xbfb8aa3b, v52
	v_mul_f32_e32 v61, 0xbfb8aa3b, v53
	v_exp_f32_e32 v60, v60
	v_exp_f32_e32 v61, v61
	v_mul_f32_e32 v63, 0xbfb8aa3b, v55
	v_exp_f32_e32 v62, v62
	v_exp_f32_e32 v63, v63
	v_add_f32_e32 v60, 1.0, v60
	v_add_f32_e32 v61, 1.0, v61
	v_rcp_f32_e32 v60, v60
	v_rcp_f32_e32 v61, v61
	v_add_f32_e32 v62, 1.0, v62
	v_add_f32_e32 v63, 1.0, v63
	v_rcp_f32_e32 v62, v62
	v_rcp_f32_e32 v63, v63
	v_pk_mul_f32 v[52:53], v[52:53], v[60:61]
	v_cvt_pk_bf16_f32 v56, v56, v57
	v_pk_mul_f32 v[48:49], v[48:49], v[52:53]
	v_pk_mul_f32 v[52:53], v[54:55], v[62:63]
	v_cvt_pk_bf16_f32 v48, v48, v49
	v_pk_mul_f32 v[50:51], v[50:51], v[52:53]
	v_cvt_pk_bf16_f32 v57, v58, v59
	v_cvt_pk_bf16_f32 v49, v50, v51
	v_mul_f32_e32 v50, 0xbfb8aa3b, v44
	v_mul_f32_e32 v51, 0xbfb8aa3b, v45
	v_mad_i64_i32 v[58:59], s[48:49], v68, s66, v[120:121]
	v_exp_f32_e32 v50, v50
	v_exp_f32_e32 v51, v51
	v_lshl_add_u64 v[58:59], v[58:59], 0, s[56:57]
	v_lshl_add_u64 v[58:59], v[58:59], 0, s[10:11]
	v_lshl_add_u64 v[58:59], v[58:59], 0, v[138:139]
	global_store_dwordx2 v[58:59], v[48:49], off offset:128
	v_add_f32_e32 v48, 1.0, v50
	v_add_f32_e32 v49, 1.0, v51
	v_mul_f32_e32 v50, 0xbfb8aa3b, v46
	v_mul_f32_e32 v51, 0xbfb8aa3b, v47
	v_exp_f32_e32 v50, v50
	v_exp_f32_e32 v51, v51
	v_rcp_f32_e32 v48, v48
	v_rcp_f32_e32 v49, v49
	v_add_f32_e32 v50, 1.0, v50
	v_add_f32_e32 v51, 1.0, v51
	v_rcp_f32_e32 v50, v50
	v_rcp_f32_e32 v51, v51
	v_pk_mul_f32 v[44:45], v[44:45], v[48:49]
	v_add_u32_e32 v52, 0x90, v152
	v_pk_mul_f32 v[40:41], v[40:41], v[44:45]
	v_pk_mul_f32 v[44:45], v[46:47], v[50:51]
	v_mul_f32_e32 v46, 0xbfb8aa3b, v38
	v_pk_mul_f32 v[42:43], v[42:43], v[44:45]
	v_mul_f32_e32 v44, 0xbfb8aa3b, v36
	v_mul_f32_e32 v45, 0xbfb8aa3b, v37
	v_exp_f32_e32 v44, v44
	v_exp_f32_e32 v45, v45
	v_mul_f32_e32 v47, 0xbfb8aa3b, v39
	v_exp_f32_e32 v46, v46
	v_exp_f32_e32 v47, v47
	v_add_f32_e32 v44, 1.0, v44
	v_add_f32_e32 v45, 1.0, v45
	v_rcp_f32_e32 v44, v44
	v_rcp_f32_e32 v45, v45
	v_add_f32_e32 v46, 1.0, v46
	v_add_f32_e32 v47, 1.0, v47
	v_rcp_f32_e32 v46, v46
	v_rcp_f32_e32 v47, v47
	v_pk_mul_f32 v[36:37], v[36:37], v[44:45]
	v_cvt_pk_bf16_f32 v40, v40, v41
	v_pk_mul_f32 v[32:33], v[32:33], v[36:37]
	v_pk_mul_f32 v[36:37], v[38:39], v[46:47]
	v_cvt_pk_bf16_f32 v32, v32, v33
	v_pk_mul_f32 v[34:35], v[34:35], v[36:37]
	v_cvt_pk_bf16_f32 v41, v42, v43
	v_cvt_pk_bf16_f32 v33, v34, v35
	v_mul_f32_e32 v34, 0xbfb8aa3b, v28
	v_mul_f32_e32 v35, 0xbfb8aa3b, v29
	v_mad_i64_i32 v[42:43], s[48:49], v52, s66, v[120:121]
	v_exp_f32_e32 v34, v34
	v_exp_f32_e32 v35, v35
	v_lshl_add_u64 v[42:43], v[42:43], 0, s[56:57]
	v_lshl_add_u64 v[42:43], v[42:43], 0, s[10:11]
	v_lshl_add_u64 v[42:43], v[42:43], 0, v[138:139]
	global_store_dwordx2 v[42:43], v[32:33], off offset:128
	v_add_f32_e32 v32, 1.0, v34
	v_add_f32_e32 v33, 1.0, v35
	v_mul_f32_e32 v34, 0xbfb8aa3b, v30
	v_mul_f32_e32 v35, 0xbfb8aa3b, v31
	v_exp_f32_e32 v34, v34
	v_exp_f32_e32 v35, v35
	v_rcp_f32_e32 v32, v32
	v_rcp_f32_e32 v33, v33
	v_add_f32_e32 v34, 1.0, v34
	v_add_f32_e32 v35, 1.0, v35
	v_rcp_f32_e32 v34, v34
	v_rcp_f32_e32 v35, v35
	v_pk_mul_f32 v[28:29], v[28:29], v[32:33]
	v_add_u32_e32 v36, 0xa0, v152
	v_pk_mul_f32 v[24:25], v[24:25], v[28:29]
	v_pk_mul_f32 v[28:29], v[30:31], v[34:35]
	v_mul_f32_e32 v30, 0xbfb8aa3b, v22
	v_pk_mul_f32 v[26:27], v[26:27], v[28:29]
	v_mul_f32_e32 v28, 0xbfb8aa3b, v20
	v_mul_f32_e32 v29, 0xbfb8aa3b, v21
	v_exp_f32_e32 v28, v28
	v_exp_f32_e32 v29, v29
	v_mul_f32_e32 v31, 0xbfb8aa3b, v23
	v_exp_f32_e32 v30, v30
	v_exp_f32_e32 v31, v31
	v_add_f32_e32 v28, 1.0, v28
	v_add_f32_e32 v29, 1.0, v29
	v_rcp_f32_e32 v28, v28
	v_rcp_f32_e32 v29, v29
	v_add_f32_e32 v30, 1.0, v30
	v_add_f32_e32 v31, 1.0, v31
	v_rcp_f32_e32 v30, v30
	v_rcp_f32_e32 v31, v31
	v_pk_mul_f32 v[20:21], v[20:21], v[28:29]
	v_cvt_pk_bf16_f32 v24, v24, v25
	v_pk_mul_f32 v[16:17], v[16:17], v[20:21]
	v_pk_mul_f32 v[20:21], v[22:23], v[30:31]
	v_cvt_pk_bf16_f32 v16, v16, v17
	v_pk_mul_f32 v[18:19], v[18:19], v[20:21]
	v_cvt_pk_bf16_f32 v25, v26, v27
	v_cvt_pk_bf16_f32 v17, v18, v19
	v_mul_f32_e32 v18, 0xbfb8aa3b, v12
	v_mul_f32_e32 v19, 0xbfb8aa3b, v13
	v_mad_i64_i32 v[26:27], s[48:49], v36, s66, v[120:121]
	v_exp_f32_e32 v18, v18
	v_exp_f32_e32 v19, v19
	v_lshl_add_u64 v[26:27], v[26:27], 0, s[56:57]
	v_lshl_add_u64 v[26:27], v[26:27], 0, s[10:11]
	v_lshl_add_u64 v[26:27], v[26:27], 0, v[138:139]
	global_store_dwordx2 v[26:27], v[16:17], off offset:128
	v_add_f32_e32 v16, 1.0, v18
	v_add_f32_e32 v17, 1.0, v19
	v_mul_f32_e32 v18, 0xbfb8aa3b, v14
	v_mul_f32_e32 v19, 0xbfb8aa3b, v15
	v_exp_f32_e32 v18, v18
	v_exp_f32_e32 v19, v19
	v_rcp_f32_e32 v16, v16
	v_rcp_f32_e32 v17, v17
	v_add_f32_e32 v18, 1.0, v18
	v_add_f32_e32 v19, 1.0, v19
	v_rcp_f32_e32 v18, v18
	v_rcp_f32_e32 v19, v19
	v_pk_mul_f32 v[12:13], v[12:13], v[16:17]
	v_add_u32_e32 v20, 0xb0, v152
	v_pk_mul_f32 v[8:9], v[8:9], v[12:13]
	v_pk_mul_f32 v[12:13], v[14:15], v[18:19]
	v_mul_f32_e32 v14, 0xbfb8aa3b, v6
	v_pk_mul_f32 v[10:11], v[10:11], v[12:13]
	v_mul_f32_e32 v12, 0xbfb8aa3b, v4
	v_mul_f32_e32 v13, 0xbfb8aa3b, v5
	v_exp_f32_e32 v12, v12
	v_exp_f32_e32 v13, v13
	v_mul_f32_e32 v15, 0xbfb8aa3b, v7
	v_exp_f32_e32 v14, v14
	v_exp_f32_e32 v15, v15
	v_add_f32_e32 v12, 1.0, v12
	v_add_f32_e32 v13, 1.0, v13
	v_rcp_f32_e32 v12, v12
	v_rcp_f32_e32 v13, v13
	v_add_f32_e32 v14, 1.0, v14
	v_add_f32_e32 v15, 1.0, v15
	v_rcp_f32_e32 v14, v14
	v_rcp_f32_e32 v15, v15
	v_cvt_pk_bf16_f32 v8, v8, v9
	v_cvt_pk_bf16_f32 v9, v10, v11
	v_mad_i64_i32 v[10:11], s[48:49], v20, s66, v[120:121]
	v_pk_mul_f32 v[4:5], v[4:5], v[12:13]
	v_lshl_add_u64 v[10:11], v[10:11], 0, s[56:57]
	v_pk_mul_f32 v[0:1], v[0:1], v[4:5]
	v_pk_mul_f32 v[4:5], v[6:7], v[14:15]
	v_lshl_add_u64 v[10:11], v[10:11], 0, s[10:11]
	v_pk_mul_f32 v[2:3], v[2:3], v[4:5]
	v_lshl_add_u64 v[10:11], v[10:11], 0, v[138:139]
	v_cvt_pk_bf16_f32 v0, v0, v1
	v_cvt_pk_bf16_f32 v1, v2, v3
	s_waitcnt vmcnt(7)
	buffer_store_dwordx4 v[166:169], v246, s[76:79], s5 offen nt
	buffer_store_dwordx4 v[170:173], v246, s[76:79], s5 offen offset:1024 nt
	buffer_store_dwordx4 v[174:177], v246, s[76:79], s5 offen offset:2048 nt
	buffer_store_dwordx4 v[178:181], v246, s[76:79], s5 offen offset:3072 nt
	buffer_store_dwordx4 v[182:185], v246, s[76:79], vcc_lo offen nt
	buffer_store_dwordx4 v[186:189], v246, s[76:79], vcc_lo offen offset:1024 nt
	buffer_store_dwordx4 v[190:193], v246, s[76:79], vcc_lo offen offset:2048 nt
	buffer_store_dwordx4 v[194:197], v246, s[76:79], vcc_lo offen offset:3072 nt
	buffer_store_dwordx4 v[198:201], v246, s[76:79], vcc_hi offen nt
	buffer_store_dwordx4 v[202:205], v246, s[76:79], vcc_hi offen offset:1024 nt
	buffer_store_dwordx4 v[206:209], v246, s[76:79], vcc_hi offen offset:2048 nt
	buffer_store_dwordx4 v[210:213], v246, s[76:79], vcc_hi offen offset:3072 nt
	s_add_u32 s5, s5, 0x30000
	s_cmp_ge_u32 s5, 0xf0000
	s_cselect_b32 s5, 0x70000000, s5
	s_andn2_b64 vcc, exec, s[6:7]
	s_mov_b64 s[6:7], -1
	global_store_dwordx2 v[122:123], v[124:125], off
	global_store_dwordx2 v[106:107], v[104:105], off
	global_store_dwordx2 v[90:91], v[88:89], off
	global_store_dwordx2 v[74:75], v[72:73], off
	global_store_dwordx2 v[58:59], v[56:57], off
	global_store_dwordx2 v[42:43], v[40:41], off
	global_store_dwordx2 v[26:27], v[24:25], off
	global_store_dwordx2 v[10:11], v[8:9], off
	global_store_dwordx2 v[10:11], v[0:1], off offset:128
	s_cbranch_vccnz .LBB0_1654
	s_andn2_b64 vcc, exec, s[22:23]
	s_cbranch_vccnz .LBB0_1653
	s_barrier
	s_branch .LBB0_1653
.LBB0_1664:
	s_waitcnt vmcnt(0)
	s_barrier
	v_readlane_b32 s78, v247, 0
	v_readlane_b32 s79, v247, 1
	v_readlane_b32 s4, v247, 2
	v_readlane_b32 s5, v247, 3
